# pp_v31 + ATTN: next unit's Q/mask loads and first two K/V tile DMAs issued under the current unit's epilogue
# baseline (speedup 1.0000x reference)
.Lpp_post:
	s_nop 2
	v_rcp_f32_e32 v3, v50
	v_rcp_f32_e32 v4, v51
	s_waitcnt vmcnt(0)
	s_cmp_eq_u32 s26, 3
	s_cbranch_scc1 .Lat_nopf
	s_cmp_eq_u32 s26, 0
	s_cselect_b32 s36, s17, s18
	s_cmp_eq_u32 s26, 2
	s_cselect_b32 s36, s19, s36
	s_lshl_b32 s36, s36, 8
	s_add_i32 s36, s36, s16
	s_add_u32 s6, s8, s36
	s_addc_u32 s7, s9, 0
	s_lshl_b64 s[6:7], s[6:7], 10
	v_lshl_add_u64 v[150:151], v[114:115], 0, s[6:7]
	s_mov_b32 s6, s36
	s_mov_b32 s7, s11
	v_lshl_add_u64 v[136:137], s[6:7], 3, v[120:121]
	s_waitcnt lgkmcnt(0)
	s_barrier
	global_load_dwordx4 v[98:101], v[150:151], off offset:32
	global_load_dwordx4 v[102:105], v[150:151], off offset:64
	global_load_dwordx4 v[106:109], v[150:151], off offset:96
	global_load_dwordx4 v[110:113], v[150:151], off
	global_load_dwordx2 v[138:139], v[136:137], off
	s_mov_b32 m0, s21
	s_nop 0
	global_load_lds_dwordx4 v[116:117], off
	s_mov_b32 m0, s22
	s_nop 0
	global_load_lds_dwordx4 v[118:119], off
	s_mov_b32 m0, s23
	s_nop 0
	global_load_lds_dwordx4 v[122:123], off
	s_mov_b32 m0, s24
	s_nop 0
	global_load_lds_dwordx4 v[124:125], off
